# P1 rebalanced: sample rows one per workgroup (wave 0 of workgroups 0..119, wave 1 of 0..7) instead of eight per workgroup on 0..15; gate rows on workgroups 120..255
# speedup vs baseline: 1.0181x; 1.0116x over previous
.LBB0_154:
	s_or_b64 exec, exec, s[2:3]
	s_mov_b32 s2, 0x45800000
	v_pk_mul_f32 v[136:137], v[134:135], s[2:3] op_sel_hi:[1,0]
	s_waitcnt lgkmcnt(0)
	v_cndmask_b32_e64 v162, v135, v137, s[8:9]
	v_cndmask_b32_e64 v140, v134, v136, s[4:5]
	v_pk_mul_f32 v[134:135], v[132:133], s[2:3] op_sel_hi:[1,0]
	s_barrier
	v_cndmask_b32_e64 v158, v133, v135, s[12:13]
	v_cndmask_b32_e64 v160, v132, v134, s[10:11]
	v_pk_mul_f32 v[132:133], v[130:131], s[2:3] op_sel_hi:[1,0]
	s_nop 0
	v_cndmask_b32_e64 v152, v131, v133, s[16:17]
	v_cndmask_b32_e64 v154, v130, v132, s[14:15]
	v_pk_mul_f32 v[130:131], v[128:129], s[2:3] op_sel_hi:[1,0]
	v_ashrrev_i32_e32 v151, 6, v144
	v_cndmask_b32_e64 v150, v128, v130, s[18:19]
	v_lshlrev_b32_e32 v128, 2, v144
	v_and_b32_e32 v145, 0xfc, v128
	v_lshl_add_u32 v149, v145, 2, 0
	v_cndmask_b32_e64 v148, v129, v131, s[20:21]
	ds_read_b128 v[128:131], v149 offset:4096
	ds_read_b128 v[132:135], v149
	v_pk_mul_f32 v[168:169], v[116:117], v[140:141] op_sel_hi:[1,0]
	v_lshl_add_u32 v116, v151, 3, s33
	v_pk_mul_f32 v[142:143], v[124:125], v[140:141] op_sel_hi:[1,0]
	v_pk_mul_f32 v[146:147], v[126:127], v[140:141] op_sel_hi:[1,0]
	s_add_u32 s10, s78, 0xd48000
	v_ashrrev_i32_e32 v117, 31, v116
	ds_read_b128 v[124:127], v149 offset:1024
	ds_read_b128 v[136:139], v149 offset:5120
	s_waitcnt lgkmcnt(2)
	v_pk_fma_f32 v[146:147], v[134:135], v[146:147], v[130:131]
	v_pk_fma_f32 v[142:143], v[132:133], v[142:143], v[128:129]
	s_addc_u32 s11, s79, 0
	v_lshlrev_b64 v[116:117], 11, v[116:117]
	v_cvt_pk_bf16_f32 v142, v142, v143
	v_cvt_pk_bf16_f32 v143, v146, v147
	v_lshl_add_u64 v[116:117], s[10:11], 0, v[116:117]
	v_mov_b32_e32 v147, 0
	v_lshlrev_b32_e32 v146, 1, v145
	v_lshl_add_u64 v[156:157], v[116:117], 0, v[146:147]
	global_store_dwordx2 v[156:157], v[142:143], off
	v_pk_mul_f32 v[112:113], v[112:113], v[140:141] op_sel_hi:[1,0]
	v_pk_mul_f32 v[114:115], v[114:115], v[140:141] op_sel_hi:[1,0]
	v_pk_mul_f32 v[164:165], v[120:121], v[140:141] op_sel_hi:[1,0]
	v_pk_mul_f32 v[166:167], v[122:123], v[140:141] op_sel_hi:[1,0]
	v_pk_mul_f32 v[170:171], v[118:119], v[140:141] op_sel_hi:[1,0]
	ds_read_b128 v[120:123], v149 offset:6144
	ds_read_b128 v[140:143], v149 offset:2048
	s_waitcnt lgkmcnt(2)
	v_pk_fma_f32 v[112:113], v[124:125], v[112:113], v[136:137]
	v_pk_fma_f32 v[114:115], v[126:127], v[114:115], v[138:139]
	v_cvt_pk_bf16_f32 v112, v112, v113
	v_pk_mul_f32 v[96:97], v[96:97], v[162:163] op_sel_hi:[1,0]
	v_cvt_pk_bf16_f32 v113, v114, v115
	global_store_dwordx2 v[156:157], v[112:113], off offset:512
	ds_read_b128 v[112:115], v149 offset:3072
	ds_read_b128 v[116:119], v149 offset:7168
	v_pk_mul_f32 v[98:99], v[98:99], v[162:163] op_sel_hi:[1,0]
	s_waitcnt lgkmcnt(2)
	v_pk_fma_f32 v[96:97], v[140:141], v[96:97], v[120:121]
	v_pk_fma_f32 v[98:99], v[142:143], v[98:99], v[122:123]
	v_cvt_pk_bf16_f32 v96, v96, v97
	v_pk_mul_f32 v[92:93], v[92:93], v[160:161] op_sel_hi:[1,0]
	v_cvt_pk_bf16_f32 v97, v98, v99
	v_pk_mul_f32 v[94:95], v[94:95], v[160:161] op_sel_hi:[1,0]
	global_store_dwordx2 v[156:157], v[96:97], off offset:3072
	v_pk_mul_f32 v[96:97], v[100:101], v[162:163] op_sel_hi:[1,0]
	v_pk_fma_f32 v[94:95], v[134:135], v[94:95], v[130:131]
	v_pk_fma_f32 v[92:93], v[132:133], v[92:93], v[128:129]
	s_movk_i32 s2, 0x1000
	s_waitcnt lgkmcnt(0)
	v_pk_fma_f32 v[96:97], v[112:113], v[96:97], v[116:117]
	v_cvt_pk_bf16_f32 v92, v92, v93
	v_cvt_pk_bf16_f32 v93, v94, v95
	v_add_co_u32_e32 v94, vcc, s2, v156
	v_pk_mul_f32 v[98:99], v[102:103], v[162:163] op_sel_hi:[1,0]
	v_cvt_pk_bf16_f32 v96, v96, v97
	s_nop 0
	v_addc_co_u32_e32 v95, vcc, 0, v157, vcc
	s_movk_i32 s2, 0x2000
	v_pk_fma_f32 v[98:99], v[114:115], v[98:99], v[118:119]
	v_pk_mul_f32 v[16:17], v[16:17], v[150:151] op_sel_hi:[1,0]
	v_cvt_pk_bf16_f32 v97, v98, v99
	global_store_dwordx2 v[156:157], v[96:97], off offset:3584
	v_add_co_u32_e32 v96, vcc, s2, v156
	v_pk_mul_f32 v[18:19], v[18:19], v[150:151] op_sel_hi:[1,0]
	s_nop 0
	v_addc_co_u32_e32 v97, vcc, 0, v157, vcc
	v_pk_fma_f32 v[18:19], v[134:135], v[18:19], v[130:131]
	v_pk_fma_f32 v[16:17], v[132:133], v[16:17], v[128:129]
	s_movk_i32 s33, 0x3000
	v_pk_mul_f32 v[4:5], v[4:5], v[150:151] op_sel_hi:[1,0]
	v_cvt_pk_bf16_f32 v16, v16, v17
	v_cvt_pk_bf16_f32 v17, v18, v19
	v_add_co_u32_e32 v18, vcc, s33, v156
	v_pk_mul_f32 v[6:7], v[6:7], v[150:151] op_sel_hi:[1,0]
	v_pk_fma_f32 v[4:5], v[112:113], v[4:5], v[116:117]
	v_addc_co_u32_e32 v19, vcc, 0, v157, vcc
	v_pk_fma_f32 v[6:7], v[114:115], v[6:7], v[118:119]
	v_cvt_pk_bf16_f32 v4, v4, v5
	v_pk_mul_f32 v[64:65], v[64:65], v[160:161] op_sel_hi:[1,0]
	v_cvt_pk_bf16_f32 v5, v6, v7
	global_store_dwordx2 v[18:19], v[4:5], off offset:1536
	v_pk_mul_f32 v[4:5], v[88:89], v[148:149] op_sel_hi:[1,0]
	v_pk_mul_f32 v[6:7], v[90:91], v[148:149] op_sel_hi:[1,0]
	v_pk_fma_f32 v[4:5], v[132:133], v[4:5], v[128:129]
	v_pk_fma_f32 v[6:7], v[134:135], v[6:7], v[130:131]
	v_cvt_pk_bf16_f32 v4, v4, v5
	v_pk_mul_f32 v[40:41], v[40:41], v[154:155] op_sel_hi:[1,0]
	v_cvt_pk_bf16_f32 v5, v6, v7
	global_store_dwordx2 v[18:19], v[4:5], off offset:2048
	v_pk_mul_f32 v[4:5], v[80:81], v[148:149] op_sel_hi:[1,0]
	v_pk_mul_f32 v[66:67], v[66:67], v[160:161] op_sel_hi:[1,0]
	v_pk_fma_f32 v[64:65], v[112:113], v[64:65], v[116:117]
	v_pk_fma_f32 v[40:41], v[140:141], v[40:41], v[120:121]
	v_pk_mul_f32 v[6:7], v[82:83], v[148:149] op_sel_hi:[1,0]
	v_pk_fma_f32 v[4:5], v[124:125], v[4:5], v[136:137]
	v_pk_fma_f32 v[66:67], v[114:115], v[66:67], v[118:119]
	v_cvt_pk_bf16_f32 v64, v64, v65
	v_pk_mul_f32 v[42:43], v[42:43], v[154:155] op_sel_hi:[1,0]
	v_cvt_pk_bf16_f32 v65, v66, v67
	v_cvt_pk_bf16_f32 v40, v40, v41
	v_pk_fma_f32 v[6:7], v[126:127], v[6:7], v[138:139]
	v_cvt_pk_bf16_f32 v4, v4, v5
	v_pk_fma_f32 v[166:167], v[142:143], v[166:167], v[122:123]
	v_cvt_pk_bf16_f32 v5, v6, v7
	v_pk_fma_f32 v[164:165], v[140:141], v[164:165], v[120:121]
	v_pk_mul_f32 v[108:109], v[108:109], v[162:163] op_sel_hi:[1,0]
	v_pk_mul_f32 v[104:105], v[104:105], v[162:163] op_sel_hi:[1,0]
	v_pk_mul_f32 v[84:85], v[84:85], v[160:161] op_sel_hi:[1,0]
	v_pk_mul_f32 v[76:77], v[76:77], v[160:161] op_sel_hi:[1,0]
	global_store_dwordx2 v[94:95], v[64:65], off offset:1536
	v_pk_mul_f32 v[64:65], v[68:69], v[158:159] op_sel_hi:[1,0]
	v_pk_mul_f32 v[60:61], v[60:61], v[158:159] op_sel_hi:[1,0]
	v_pk_mul_f32 v[56:57], v[56:57], v[158:159] op_sel_hi:[1,0]
	v_pk_mul_f32 v[52:53], v[52:53], v[158:159] op_sel_hi:[1,0]
	v_pk_mul_f32 v[48:49], v[48:49], v[154:155] op_sel_hi:[1,0]
	v_pk_mul_f32 v[44:45], v[44:45], v[154:155] op_sel_hi:[1,0]
	v_pk_fma_f32 v[42:43], v[142:143], v[42:43], v[122:123]
	v_pk_mul_f32 v[36:37], v[36:37], v[154:155] op_sel_hi:[1,0]
	v_cvt_pk_bf16_f32 v41, v42, v43
	global_store_dwordx2 v[96:97], v[40:41], off offset:1024
	v_pk_mul_f32 v[32:33], v[32:33], v[152:153] op_sel_hi:[1,0]
	v_pk_mul_f32 v[28:29], v[28:29], v[152:153] op_sel_hi:[1,0]
	v_pk_mul_f32 v[24:25], v[24:25], v[152:153] op_sel_hi:[1,0]
	v_pk_mul_f32 v[20:21], v[20:21], v[152:153] op_sel_hi:[1,0]
	v_pk_mul_f32 v[12:13], v[12:13], v[150:151] op_sel_hi:[1,0]
	v_pk_mul_f32 v[8:9], v[8:9], v[150:151] op_sel_hi:[1,0]
	global_store_dwordx2 v[18:19], v[4:5], off offset:2560
	v_pk_mul_f32 v[4:5], v[72:73], v[148:149] op_sel_hi:[1,0]
	v_pk_mul_f32 v[0:1], v[0:1], v[148:149] op_sel_hi:[1,0]
	v_mul_u32_u24_e32 v40, 0x78, v151
	v_add_u32_e32 v40, s96, v40
	s_cmp_ge_u32 s96, 0x78
	s_cselect_b32 s100, 0x80, 0
	v_min_u32_e32 v240, 1, v151
	v_sub_u32_e32 v240, 1, v240
	v_mad_u32_u24 v40, v240, s100, v40
	s_movk_i32 s2, 0x80
	v_cvt_pk_bf16_f32 v164, v164, v165
	v_cvt_pk_bf16_f32 v165, v166, v167
	v_pk_fma_f32 v[166:167], v[112:113], v[168:169], v[116:117]
	v_pk_mul_f32 v[110:111], v[110:111], v[162:163] op_sel_hi:[1,0]
	v_pk_fma_f32 v[108:109], v[132:133], v[108:109], v[128:129]
	v_pk_mul_f32 v[106:107], v[106:107], v[162:163] op_sel_hi:[1,0]
	v_pk_fma_f32 v[104:105], v[124:125], v[104:105], v[136:137]
	v_pk_mul_f32 v[86:87], v[86:87], v[160:161] op_sel_hi:[1,0]
	v_pk_fma_f32 v[84:85], v[124:125], v[84:85], v[136:137]
	v_pk_mul_f32 v[78:79], v[78:79], v[160:161] op_sel_hi:[1,0]
	v_pk_fma_f32 v[76:77], v[140:141], v[76:77], v[120:121]
	v_pk_mul_f32 v[66:67], v[70:71], v[158:159] op_sel_hi:[1,0]
	v_pk_fma_f32 v[64:65], v[132:133], v[64:65], v[128:129]
	v_pk_mul_f32 v[62:63], v[62:63], v[158:159] op_sel_hi:[1,0]
	v_pk_fma_f32 v[60:61], v[124:125], v[60:61], v[136:137]
	v_pk_mul_f32 v[58:59], v[58:59], v[158:159] op_sel_hi:[1,0]
	v_pk_fma_f32 v[56:57], v[140:141], v[56:57], v[120:121]
	v_pk_mul_f32 v[54:55], v[54:55], v[158:159] op_sel_hi:[1,0]
	v_pk_fma_f32 v[52:53], v[112:113], v[52:53], v[116:117]
	v_pk_mul_f32 v[50:51], v[50:51], v[154:155] op_sel_hi:[1,0]
	v_pk_fma_f32 v[48:49], v[132:133], v[48:49], v[128:129]
	v_pk_mul_f32 v[46:47], v[46:47], v[154:155] op_sel_hi:[1,0]
	v_pk_fma_f32 v[44:45], v[124:125], v[44:45], v[136:137]
	v_pk_mul_f32 v[38:39], v[38:39], v[154:155] op_sel_hi:[1,0]
	v_pk_fma_f32 v[36:37], v[112:113], v[36:37], v[116:117]
	v_pk_mul_f32 v[34:35], v[34:35], v[152:153] op_sel_hi:[1,0]
	v_pk_fma_f32 v[32:33], v[132:133], v[32:33], v[128:129]
	v_pk_mul_f32 v[30:31], v[30:31], v[152:153] op_sel_hi:[1,0]
	v_pk_fma_f32 v[28:29], v[124:125], v[28:29], v[136:137]
	v_pk_mul_f32 v[26:27], v[26:27], v[152:153] op_sel_hi:[1,0]
	v_pk_fma_f32 v[24:25], v[140:141], v[24:25], v[120:121]
	v_pk_mul_f32 v[22:23], v[22:23], v[152:153] op_sel_hi:[1,0]
	v_pk_fma_f32 v[20:21], v[112:113], v[20:21], v[116:117]
	v_pk_mul_f32 v[14:15], v[14:15], v[150:151] op_sel_hi:[1,0]
	v_pk_fma_f32 v[12:13], v[124:125], v[12:13], v[136:137]
	v_pk_mul_f32 v[10:11], v[10:11], v[150:151] op_sel_hi:[1,0]
	v_pk_fma_f32 v[8:9], v[140:141], v[8:9], v[120:121]
	v_pk_mul_f32 v[6:7], v[74:75], v[148:149] op_sel_hi:[1,0]
	v_pk_fma_f32 v[4:5], v[140:141], v[4:5], v[120:121]
	v_pk_mul_f32 v[2:3], v[2:3], v[148:149] op_sel_hi:[1,0]
	v_pk_fma_f32 v[0:1], v[112:113], v[0:1], v[116:117]
	v_cmp_gt_i32_e32 vcc, s2, v40
	global_store_dwordx2 v[156:157], v[164:165], off offset:1024
	v_pk_fma_f32 v[164:165], v[114:115], v[170:171], v[118:119]
	v_cvt_pk_bf16_f32 v166, v166, v167
	v_pk_fma_f32 v[110:111], v[134:135], v[110:111], v[130:131]
	v_cvt_pk_bf16_f32 v167, v164, v165
	global_store_dwordx2 v[156:157], v[166:167], off offset:1536
	v_cvt_pk_bf16_f32 v108, v108, v109
	v_cvt_pk_bf16_f32 v109, v110, v111
	global_store_dwordx2 v[156:157], v[108:109], off offset:2048
	v_pk_fma_f32 v[106:107], v[126:127], v[106:107], v[138:139]
	v_cvt_pk_bf16_f32 v104, v104, v105
	global_store_dwordx2 v[96:97], v[92:93], off offset:-4096
	v_cvt_pk_bf16_f32 v105, v106, v107
	global_store_dwordx2 v[156:157], v[104:105], off offset:2560
	v_pk_fma_f32 v[86:87], v[126:127], v[86:87], v[138:139]
	v_cvt_pk_bf16_f32 v84, v84, v85
	v_pk_fma_f32 v[78:79], v[142:143], v[78:79], v[122:123]
	v_cvt_pk_bf16_f32 v85, v86, v87
	global_store_dwordx2 v[94:95], v[84:85], off offset:512
	v_cvt_pk_bf16_f32 v76, v76, v77
	v_cvt_pk_bf16_f32 v77, v78, v79
	global_store_dwordx2 v[94:95], v[76:77], off offset:1024
	v_pk_fma_f32 v[66:67], v[134:135], v[66:67], v[130:131]
	v_cvt_pk_bf16_f32 v64, v64, v65
	v_pk_fma_f32 v[62:63], v[126:127], v[62:63], v[138:139]
	v_cvt_pk_bf16_f32 v65, v66, v67
	global_store_dwordx2 v[94:95], v[64:65], off offset:2048
	v_cvt_pk_bf16_f32 v60, v60, v61
	v_cvt_pk_bf16_f32 v61, v62, v63
	global_store_dwordx2 v[94:95], v[60:61], off offset:2560
	v_pk_fma_f32 v[58:59], v[142:143], v[58:59], v[122:123]
	v_cvt_pk_bf16_f32 v56, v56, v57
	v_pk_fma_f32 v[54:55], v[114:115], v[54:55], v[118:119]
	v_cvt_pk_bf16_f32 v57, v58, v59
	global_store_dwordx2 v[94:95], v[56:57], off offset:3072
	v_cvt_pk_bf16_f32 v52, v52, v53
	v_cvt_pk_bf16_f32 v53, v54, v55
	global_store_dwordx2 v[94:95], v[52:53], off offset:3584
	v_pk_fma_f32 v[50:51], v[134:135], v[50:51], v[130:131]
	v_cvt_pk_bf16_f32 v48, v48, v49
	v_pk_fma_f32 v[46:47], v[126:127], v[46:47], v[138:139]
	v_cvt_pk_bf16_f32 v49, v50, v51
	global_store_dwordx2 v[96:97], v[48:49], off
	v_cvt_pk_bf16_f32 v44, v44, v45
	v_cvt_pk_bf16_f32 v45, v46, v47
	global_store_dwordx2 v[96:97], v[44:45], off offset:512
	v_pk_fma_f32 v[38:39], v[114:115], v[38:39], v[118:119]
	v_cvt_pk_bf16_f32 v36, v36, v37
	v_pk_fma_f32 v[34:35], v[134:135], v[34:35], v[130:131]
	v_cvt_pk_bf16_f32 v37, v38, v39
	global_store_dwordx2 v[96:97], v[36:37], off offset:1536
	v_cvt_pk_bf16_f32 v32, v32, v33
	v_cvt_pk_bf16_f32 v33, v34, v35
	global_store_dwordx2 v[96:97], v[32:33], off offset:2048
	v_pk_fma_f32 v[30:31], v[126:127], v[30:31], v[138:139]
	v_cvt_pk_bf16_f32 v28, v28, v29
	v_pk_fma_f32 v[26:27], v[142:143], v[26:27], v[122:123]
	v_cvt_pk_bf16_f32 v29, v30, v31
	global_store_dwordx2 v[96:97], v[28:29], off offset:2560
	v_cvt_pk_bf16_f32 v24, v24, v25
	v_cvt_pk_bf16_f32 v25, v26, v27
	global_store_dwordx2 v[96:97], v[24:25], off offset:3072
	v_pk_fma_f32 v[22:23], v[114:115], v[22:23], v[118:119]
	v_cvt_pk_bf16_f32 v20, v20, v21
	global_store_dwordx2 v[18:19], v[16:17], off
	v_cvt_pk_bf16_f32 v21, v22, v23
	global_store_dwordx2 v[96:97], v[20:21], off offset:3584
	v_pk_fma_f32 v[14:15], v[126:127], v[14:15], v[138:139]
	v_cvt_pk_bf16_f32 v12, v12, v13
	v_pk_fma_f32 v[10:11], v[142:143], v[10:11], v[122:123]
	v_cvt_pk_bf16_f32 v13, v14, v15
	global_store_dwordx2 v[18:19], v[12:13], off offset:512
	v_cvt_pk_bf16_f32 v8, v8, v9
	v_cvt_pk_bf16_f32 v9, v10, v11
	global_store_dwordx2 v[18:19], v[8:9], off offset:1024
	v_pk_fma_f32 v[6:7], v[142:143], v[6:7], v[122:123]
	v_cvt_pk_bf16_f32 v4, v4, v5
	v_pk_fma_f32 v[2:3], v[114:115], v[2:3], v[118:119]
	v_cvt_pk_bf16_f32 v5, v6, v7
	global_store_dwordx2 v[18:19], v[4:5], off offset:3072
	v_cvt_pk_bf16_f32 v0, v0, v1
	v_cvt_pk_bf16_f32 v1, v2, v3
	global_store_dwordx2 v[18:19], v[0:1], off offset:3584
	s_and_saveexec_b64 s[2:3], vcc
	s_cbranch_execz .LBB0_157
	s_load_dwordx16 s[36:51], s[0:1], 0x0
	v_or_b32_e32 v0, 0x100, v145
	v_lshl_add_u64 v[42:43], s[10:11], 0, v[146:147]
	v_lshlrev_b32_e32 v146, 2, v0
	v_or_b32_e32 v2, 0x200, v145
	s_waitcnt lgkmcnt(0)
	s_mov_b64 s[24:25], s[48:49]
	s_add_u32 s6, s24, 0x1000
	s_addc_u32 s7, s25, 0
	s_mov_b64 s[12:13], s[36:37]
	v_lshl_add_u64 v[52:53], s[6:7], 0, v[146:147]
	v_lshlrev_b32_e32 v146, 2, v2
	v_or_b32_e32 v4, 0x300, v145
	s_mov_b64 s[14:15], s[38:39]
	s_mov_b64 s[26:27], s[50:51]
	s_add_u32 s4, s0, 0xb0
	v_lshlrev_b32_e32 v44, 2, v145
	v_mov_b32_e32 v45, v147
	v_lshl_add_u64 v[54:55], s[6:7], 0, v[146:147]
	v_lshlrev_b32_e32 v146, 2, v4
	s_addc_u32 s5, s1, 0
	v_lshl_add_u64 v[46:47], s[24:25], 0, v[44:45]
	v_lshl_add_u64 v[48:49], s[6:7], 0, v[44:45]
	v_lshl_add_u64 v[50:51], s[26:27], 0, v[44:45]
	v_lshl_add_u64 v[56:57], s[6:7], 0, v[146:147]
	v_lshl_add_u64 v[58:59], s[14:15], 0, v[44:45]
	s_mov_b64 s[6:7], 0
	s_mov_b64 s[8:9], 0x18000
	s_mov_b64 s[12:13], 0x19000
	s_mov_b64 s[14:15], 0x1b0000
	s_mov_b64 s[16:17], 0x1b1000
	s_mov_b64 s[18:19], 0x348000
	s_mov_b64 s[20:21], 0x349000
	s_mov_b64 s[24:25], 0x4e0000
	s_mov_b64 s[26:27], 0x4e1000
	s_mov_b64 s[28:29], 0x678000
	s_mov_b64 s[30:31], 0x679000
	s_mov_b64 s[34:35], 0x810000
	s_mov_b64 s[36:37], 0x811000
	s_mov_b64 s[38:39], 0x9a8000
	s_mov_b64 s[40:41], 0x9a9000
	s_mov_b64 s[42:43], 0xb40000
	s_mov_b64 s[44:45], 0xb41000
	v_lshlrev_b32_e32 v146, 2, v0
	v_lshlrev_b32_e32 v60, 2, v2
	v_lshlrev_b32_e32 v62, 2, v4
	v_mov_b32_e32 v104, 0x358637bd
	s_mov_b32 s48, 0x800000
	s_mov_b64 s[46:47], 0x2000000
	s_brev_b32 s49, 64
	s_movk_i32 s50, 0x7f
